# phase_fin loop: all 23 loads of an iteration requested up front into dead registers (one round trip per iteration instead of five)
# speedup vs baseline: 1.0359x; 1.0062x over previous
.LBB0_1418:
	s_nop 1
	v_mul_hi_i32 v0, v72, s85
	v_lshrrev_b32_e32 v1, 31, v0
	v_add_u32_e32 v62, v0, v1
	v_mul_lo_u32 v0, v62, 6
	v_sub_u32_e32 v0, v72, v0
	v_readlane_b32 s2, v253, 28
	v_lshl_or_b32 v64, v0, 6, v50
	v_readlane_b32 s3, v253, 29
	v_ashrrev_i32_e32 v65, 31, v64
	s_mov_b32 s1, 0x18000
	v_mov_b64_e32 v[0:1], s[2:3]
	v_mad_i64_i32 v[2:3], s[2:3], v62, s77, v[0:1]
	v_lshlrev_b64 v[0:1], 1, v[64:65]
	v_cmp_gt_i32_e32 vcc, s1, v72
	v_lshl_add_u64 v[2:3], v[2:3], 0, v[0:1]
	s_mov_b32 s1, 0x1800000
	v_cndmask_b32_e32 v5, v243, v244, vcc
	global_load_dwordx4 v[6:9], v[2:3], off
	v_add_co_u32_e32 v2, vcc, s1, v2
	v_readlane_b32 s2, v251, 60
	s_nop 0
	v_addc_co_u32_e32 v3, vcc, 0, v3, vcc
	global_load_dwordx4 v[10:13], v[2:3], off
	v_readlane_b32 s3, v251, 61
	v_readlane_b32 s100, v254, 50
	v_and_b32_e32 v103, v5, v62
	v_readlane_b32 s101, v254, 51
	v_mov_b64_e32 v[2:3], s[2:3]
	v_mad_i64_i32 v[2:3], s[2:3], v62, s31, v[2:3]
	v_cmp_ne_u32_e32 vcc, 0, v103
	v_cmp_ne_u32_e64 s[38:39], v103, v5
	v_lshl_add_u64 v[66:67], v[2:3], 0, v[0:1]
	global_load_dwordx4 v[86:89], v[66:67], off
	global_load_dwordx4 v[90:93], v[66:67], off offset:768
	global_load_dwordx4 v[94:97], v[66:67], off offset:1536
	v_mov_b32_e32 v114, 0
	v_mov_b32_e32 v115, 0
	v_mov_b32_e32 v116, 0
	v_mov_b32_e32 v117, 0
	v_mov_b32_e32 v122, 0
	v_mov_b32_e32 v123, 0
	v_mov_b32_e32 v124, 0
	v_mov_b32_e32 v125, 0
	v_mov_b32_e32 v126, 0
	v_mov_b32_e32 v127, 0
	v_mov_b32_e32 v128, 0
	v_mov_b32_e32 v129, 0
	s_and_saveexec_b64 s[2:3], vcc
	global_load_dwordx4 v[114:117], v[66:67], off offset:-2304
	global_load_dwordx4 v[122:125], v[66:67], off offset:-1536
	global_load_dwordx4 v[126:129], v[66:67], off offset:-768
	s_or_b64 exec, exec, s[2:3]
	v_mov_b32_e32 v130, 0
	v_mov_b32_e32 v131, 0
	v_mov_b32_e32 v132, 0
	v_mov_b32_e32 v133, 0
	v_mov_b32_e32 v164, 0
	v_mov_b32_e32 v165, 0
	v_mov_b32_e32 v166, 0
	v_mov_b32_e32 v167, 0
	v_mov_b32_e32 v168, 0
	v_mov_b32_e32 v169, 0
	v_mov_b32_e32 v170, 0
	v_mov_b32_e32 v171, 0
	s_and_saveexec_b64 s[2:3], s[38:39]
	global_load_dwordx4 v[130:133], v[66:67], off offset:2304
	global_load_dwordx4 v[164:167], v[66:67], off offset:3072
	global_load_dwordx4 v[168:171], v[66:67], off offset:3840
	s_or_b64 exec, exec, s[2:3]
	v_readlane_b32 s1, v255, 9
	v_lshl_add_u64 v[70:71], v[64:65], 2, s[100:101]
	global_load_dwordx4 v[172:175], v[70:71], off offset:16
	global_load_dwordx4 v[176:179], v[70:71], off
	global_load_dwordx4 v[180:183], v[70:71], off offset:1552
	global_load_dwordx4 v[196:199], v[70:71], off offset:1536
	global_load_dwordx4 v[200:203], v[70:71], off offset:3088
	global_load_dwordx4 v[204:207], v[70:71], off offset:3072
	v_add_u32_e32 v104, s1, v64
	v_ashrrev_i32_e32 v105, 31, v104
	v_lshlrev_b64 v[104:105], 2, v[104:105]
	v_readlane_b32 s8, v251, 34
	v_readlane_b32 s9, v251, 35
	v_readlane_b32 s10, v251, 36
	v_readlane_b32 s11, v251, 37
	v_readlane_b32 s12, v251, 38
	v_readlane_b32 s13, v251, 39
	v_readlane_b32 s14, v251, 40
	v_readlane_b32 s15, v251, 41
	v_readlane_b32 s16, v251, 42
	v_readlane_b32 s17, v251, 43
	v_readlane_b32 s18, v251, 44
	v_readlane_b32 s19, v251, 45
	v_readlane_b32 s20, v251, 46
	v_readlane_b32 s21, v251, 47
	v_readlane_b32 s22, v251, 48
	v_readlane_b32 s23, v251, 49
	s_mov_b64 s[12:13], s[16:17]
	s_mov_b64 s[14:15], s[18:19]
	s_mov_b64 s[16:17], s[20:21]
	s_mov_b64 s[18:19], s[22:23]
	v_ashrrev_i32_e32 v63, 31, v62
	v_lshl_add_u64 v[248:249], s[16:17], 0, v[104:105]
	global_load_dwordx4 v[208:211], v[248:249], off
	global_load_dwordx4 v[212:215], v[248:249], off offset:16
	v_lshlrev_b64 v[248:249], 11, v[62:63]
	v_lshl_add_u64 v[248:249], s[92:93], 0, v[248:249]
	v_lshl_add_u64 v[248:249], v[64:65], 1, v[248:249]
	s_mov_b32 s1, 0x2c00000
	v_add_co_u32_e32 v62, vcc, s1, v248
	s_nop 1
	v_addc_co_u32_e32 v63, vcc, 0, v249, vcc
	global_load_dwordx2 v[118:119], v[62:63], off offset:1280
	global_load_dwordx2 v[134:135], v[62:63], off offset:1288
	v_lshl_add_u64 v[248:249], s[18:19], 0, v[104:105]
	v_lshl_add_u64 v[98:99], s[88:89], 0, v[104:105]
	global_load_dwordx4 v[216:219], v[248:249], off offset:16
	global_load_dwordx4 v[220:223], v[248:249], off
	global_load_dwordx4 v[224:227], v[98:99], off offset:16
	global_load_dwordx4 v[228:231], v[98:99], off
	s_waitcnt vmcnt(23)
	v_and_b32_e32 v2, 0xffff0000, v9
	v_lshlrev_b32_e32 v3, 16, v9
	v_and_b32_e32 v14, 0xffff0000, v13
	v_lshlrev_b32_e32 v15, 16, v13
	v_pk_add_f32 v[2:3], v[2:3], v[14:15]
	v_and_b32_e32 v14, 0xffff0000, v8
	v_lshlrev_b32_e32 v15, 16, v8
	v_and_b32_e32 v8, 0xffff0000, v12
	v_lshlrev_b32_e32 v9, 16, v12
	v_pk_add_f32 v[8:9], v[14:15], v[8:9]
	v_and_b32_e32 v12, 0xffff0000, v7
	v_lshlrev_b32_e32 v13, 16, v7
	v_and_b32_e32 v14, 0xffff0000, v11
	v_lshlrev_b32_e32 v15, 16, v11
	v_pk_add_f32 v[12:13], v[12:13], v[14:15]
	v_lshlrev_b32_e32 v14, 16, v6
	v_and_b32_e32 v15, 0xffff0000, v6
	v_lshlrev_b32_e32 v6, 16, v10
	v_and_b32_e32 v7, 0xffff0000, v10
	v_pk_add_f32 v[6:7], v[14:15], v[6:7]
	s_nop 0
	v_add_f32_e32 v4, 0, v6
	v_add_f32_e32 v4, v7, v4
	v_add_f32_e32 v4, v13, v4
	v_add_f32_e32 v4, v12, v4
	v_add_f32_e32 v4, v9, v4
	v_add_f32_e32 v4, v8, v4
	v_add_f32_e32 v4, v3, v4
	v_add_f32_e32 v4, v2, v4
	s_nop 1
	v_add_f32_dpp v4, v4, v4 quad_perm:[1,0,3,2] row_mask:0xf bank_mask:0xf bound_ctrl:1
	s_nop 1
	v_add_f32_dpp v4, v4, v4 quad_perm:[2,3,0,1] row_mask:0xf bank_mask:0xf bound_ctrl:1
	s_nop 1
	v_add_f32_dpp v4, v4, v4 row_half_mirror row_mask:0xf bank_mask:0xf bound_ctrl:1
	v_mul_f32_e32 v4, 0x3c800000, v4
	v_pk_add_f32 v[60:61], v[6:7], v[4:5] op_sel_hi:[1,0] neg_lo:[0,1] neg_hi:[0,1]
	v_pk_add_f32 v[58:59], v[12:13], v[4:5] op_sel_hi:[1,0] neg_lo:[0,1] neg_hi:[0,1]
	v_pk_mul_f32 v[6:7], v[60:61], v[60:61]
	v_pk_mul_f32 v[10:11], v[58:59], v[58:59]
	v_pk_add_f32 v[56:57], v[8:9], v[4:5] op_sel_hi:[1,0] neg_lo:[0,1] neg_hi:[0,1]
	v_pk_add_f32 v[48:49], v[2:3], v[4:5] op_sel_hi:[1,0] neg_lo:[0,1] neg_hi:[0,1]
	v_add_f32_e32 v4, v6, v7
	v_add_f32_e32 v4, v11, v4
	v_pk_mul_f32 v[8:9], v[56:57], v[56:57]
	v_add_f32_e32 v4, v10, v4
	v_add_f32_e32 v4, v9, v4
	v_pk_mul_f32 v[2:3], v[48:49], v[48:49]
	v_add_f32_e32 v4, v8, v4
	v_add_f32_e32 v3, v3, v4
	v_add_f32_e32 v2, v2, v3
	s_nop 1
	v_add_f32_dpp v2, v2, v2 quad_perm:[1,0,3,2] row_mask:0xf bank_mask:0xf bound_ctrl:1
	s_nop 1
	v_add_f32_dpp v73, v2, v2 quad_perm:[2,3,0,1] row_mask:0xf bank_mask:0xf bound_ctrl:1
	s_nop 1
	v_mov_b32_dpp v74, v73 row_half_mirror row_mask:0xf bank_mask:0xf bound_ctrl:1
	s_waitcnt vmcnt(10)
	v_cvt_f32_f16_e32 v75, v126
	v_cvt_f32_f16_sdwa v76, v126 dst_sel:DWORD dst_unused:UNUSED_PAD src0_sel:WORD_1
	v_cvt_f32_f16_e32 v77, v127
	v_cvt_f32_f16_sdwa v78, v127 dst_sel:DWORD dst_unused:UNUSED_PAD src0_sel:WORD_1
	v_cvt_f32_f16_e32 v66, v122
	v_cvt_f32_f16_sdwa v67, v122 dst_sel:DWORD dst_unused:UNUSED_PAD src0_sel:WORD_1
	v_cvt_f32_f16_e32 v68, v123
	v_cvt_f32_f16_sdwa v69, v123 dst_sel:DWORD dst_unused:UNUSED_PAD src0_sel:WORD_1
	v_cvt_f32_f16_sdwa v41, v124 dst_sel:DWORD dst_unused:UNUSED_PAD src0_sel:WORD_1
	v_cvt_f32_f16_e32 v40, v124
	v_cvt_f32_f16_sdwa v53, v125 dst_sel:DWORD dst_unused:UNUSED_PAD src0_sel:WORD_1
	v_cvt_f32_f16_e32 v52, v125
	v_cvt_f32_f16_sdwa v43, v92 dst_sel:DWORD dst_unused:UNUSED_PAD src0_sel:WORD_1
	v_cvt_f32_f16_e32 v42, v92
	v_cvt_f32_f16_e32 v34, v164
	v_cvt_f32_f16_sdwa v28, v164 dst_sel:DWORD dst_unused:UNUSED_PAD src0_sel:WORD_1
	v_cvt_f32_f16_e32 v79, v128
	v_cvt_f32_f16_sdwa v80, v128 dst_sel:DWORD dst_unused:UNUSED_PAD src0_sel:WORD_1
	v_cvt_f32_f16_e32 v81, v129
	v_cvt_f32_f16_sdwa v82, v129 dst_sel:DWORD dst_unused:UNUSED_PAD src0_sel:WORD_1
	v_cvt_f32_f16_sdwa v55, v93 dst_sel:DWORD dst_unused:UNUSED_PAD src0_sel:WORD_1
	v_cvt_f32_f16_e32 v54, v93
	v_cvt_f32_f16_e32 v35, v165
	v_cvt_f32_f16_sdwa v29, v165 dst_sel:DWORD dst_unused:UNUSED_PAD src0_sel:WORD_1
	v_add_f32_e32 v28, v67, v28
	v_fma_mix_f32 v28, v28, s76, -v90 op_sel:[0,0,1] op_sel_hi:[0,0,1]
	v_fma_mix_f32 v84, v197, v28, v90 op_sel:[0,0,1] op_sel_hi:[0,0,1]
	v_add_f32_e32 v28, v68, v35
	v_fma_mix_f32 v28, v28, s76, -v91 op_sel_hi:[0,0,1]
	v_fma_mix_f32 v35, v198, v28, v91 op_sel_hi:[0,0,1]
	v_add_f32_e32 v28, v69, v29
	v_fma_mix_f32 v28, v28, s76, -v91 op_sel:[0,0,1] op_sel_hi:[0,0,1]
	v_fma_mix_f32 v33, v199, v28, v91 op_sel:[0,0,1] op_sel_hi:[0,0,1]
	v_cvt_f32_f16_sdwa v29, v166 dst_sel:DWORD dst_unused:UNUSED_PAD src0_sel:WORD_1
	v_cvt_f32_f16_e32 v28, v166
	v_add_f32_e32 v34, v66, v34
	v_fma_mix_f32 v34, v34, s76, -v90 op_sel_hi:[0,0,1]
	v_fma_mix_f32 v83, v196, v34, v90 op_sel_hi:[0,0,1]
	v_pk_add_f32 v[28:29], v[40:41], v[28:29]
	v_cvt_f32_f16_e32 v30, v96
	v_pk_fma_f32 v[28:29], v[28:29], 0.5, v[42:43] op_sel_hi:[1,0,1] neg_lo:[0,0,1] neg_hi:[0,0,1]
	v_cvt_f32_f16_sdwa v34, v96 dst_sel:DWORD dst_unused:UNUSED_PAD src0_sel:WORD_1
	v_pk_fma_f32 v[66:67], v[28:29], v[180:181], v[42:43]
	v_cvt_f32_f16_sdwa v29, v167 dst_sel:DWORD dst_unused:UNUSED_PAD src0_sel:WORD_1
	v_cvt_f32_f16_e32 v28, v167
	v_cvt_f32_f16_e32 v32, v97
	v_cvt_f32_f16_sdwa v31, v114 dst_sel:DWORD dst_unused:UNUSED_PAD src0_sel:WORD_1
	v_cvt_f32_f16_e32 v37, v115
	v_pk_add_f32 v[28:29], v[52:53], v[28:29]
	v_cvt_f32_f16_e32 v22, v117
	v_pk_fma_f32 v[28:29], v[28:29], 0.5, v[54:55] op_sel_hi:[1,0,1] neg_lo:[0,0,1] neg_hi:[0,0,1]
	v_cvt_f32_f16_sdwa v45, v89 dst_sel:DWORD dst_unused:UNUSED_PAD src0_sel:WORD_1
	v_pk_fma_f32 v[68:69], v[28:29], v[182:183], v[54:55]
	v_cvt_f32_f16_sdwa v28, v97 dst_sel:DWORD dst_unused:UNUSED_PAD src0_sel:WORD_1
	v_cvt_f32_f16_e32 v29, v114
	v_cvt_f32_f16_sdwa v39, v115 dst_sel:DWORD dst_unused:UNUSED_PAD src0_sel:WORD_1
	v_cvt_f32_f16_sdwa v9, v116 dst_sel:DWORD dst_unused:UNUSED_PAD src0_sel:WORD_1
	v_cvt_f32_f16_e32 v8, v116
	v_cvt_f32_f16_sdwa v23, v117 dst_sel:DWORD dst_unused:UNUSED_PAD src0_sel:WORD_1
	v_cvt_f32_f16_sdwa v11, v88 dst_sel:DWORD dst_unused:UNUSED_PAD src0_sel:WORD_1
	v_cvt_f32_f16_e32 v10, v88
	v_cvt_f32_f16_e32 v2, v130
	v_cvt_f32_f16_e32 v44, v89
	v_cvt_f32_f16_sdwa v3, v130 dst_sel:DWORD dst_unused:UNUSED_PAD src0_sel:WORD_1
	v_cvt_f32_f16_e32 v4, v131
	v_add_f32_e32 v2, v29, v2
	v_fma_mix_f32 v2, v2, s76, -v86 op_sel_hi:[0,0,1]
	v_cvt_f32_f16_sdwa v5, v131 dst_sel:DWORD dst_unused:UNUSED_PAD src0_sel:WORD_1
	v_fma_mix_f32 v16, v176, v2, v86 op_sel_hi:[0,0,1]
	v_add_f32_e32 v2, v31, v3
	v_fma_mix_f32 v2, v2, s76, -v86 op_sel:[0,0,1] op_sel_hi:[0,0,1]
	v_fma_mix_f32 v29, v177, v2, v86 op_sel:[0,0,1] op_sel_hi:[0,0,1]
	v_add_f32_e32 v0, v37, v4
	v_fma_mix_f32 v0, v0, s76, -v87 op_sel_hi:[0,0,1]
	v_fma_mix_f32 v37, v178, v0, v87 op_sel_hi:[0,0,1]
	v_add_f32_e32 v0, v39, v5
	v_fma_mix_f32 v0, v0, s76, -v87 op_sel:[0,0,1] op_sel_hi:[0,0,1]
	v_fma_mix_f32 v39, v179, v0, v87 op_sel:[0,0,1] op_sel_hi:[0,0,1]
	v_cvt_f32_f16_sdwa v1, v132 dst_sel:DWORD dst_unused:UNUSED_PAD src0_sel:WORD_1
	v_cvt_f32_f16_e32 v0, v132
	s_mov_b32 s1, 0x800000
	v_cvt_f32_f16_e32 v17, v170
	v_cvt_f32_f16_sdwa v18, v170 dst_sel:DWORD dst_unused:UNUSED_PAD src0_sel:WORD_1
	v_pk_add_f32 v[0:1], v[8:9], v[0:1]
	v_cvt_f32_f16_e32 v19, v171
	v_pk_fma_f32 v[0:1], v[0:1], 0.5, v[10:11] op_sel_hi:[1,0,1] neg_lo:[0,0,1] neg_hi:[0,0,1]
	v_pk_fma_f32 v[8:9], v[0:1], v[172:173], v[10:11]
	v_cvt_f32_f16_sdwa v1, v133 dst_sel:DWORD dst_unused:UNUSED_PAD src0_sel:WORD_1
	v_cvt_f32_f16_e32 v0, v133
	v_cvt_f32_f16_e32 v12, v168
	v_cvt_f32_f16_sdwa v13, v168 dst_sel:DWORD dst_unused:UNUSED_PAD src0_sel:WORD_1
	v_pk_add_f32 v[0:1], v[22:23], v[0:1]
	v_add_f32_e32 v12, v75, v12
	v_pk_fma_f32 v[0:1], v[0:1], 0.5, v[44:45] op_sel_hi:[1,0,1] neg_lo:[0,0,1] neg_hi:[0,0,1]
	v_fma_mix_f32 v54, v12, s76, -v94 op_sel_hi:[0,0,1]
	v_pk_fma_f32 v[10:11], v[0:1], v[174:175], v[44:45]
	v_cvt_f32_f16_e32 v14, v169
	v_add_f32_e32 v0, v73, v74
	v_cvt_f32_f16_sdwa v15, v169 dst_sel:DWORD dst_unused:UNUSED_PAD src0_sel:WORD_1
	v_fmamk_f32 v0, v0, 0x3c800000, v247
	v_cmp_gt_f32_e32 vcc, s1, v0
	v_mul_f32_e32 v1, 0x4b800000, v0
	v_add_f32_e32 v12, v76, v13
	v_cndmask_b32_e32 v0, v0, v1, vcc
	v_fma_mix_f32 v52, v12, s76, -v94 op_sel:[0,0,1] op_sel_hi:[0,0,1]
	v_add_f32_e32 v12, v77, v14
	v_rsq_f32_e32 v0, v0
	v_cvt_f32_f16_sdwa v22, v171 dst_sel:DWORD dst_unused:UNUSED_PAD src0_sel:WORD_1
	v_fma_mix_f32 v46, v12, s76, -v95 op_sel_hi:[0,0,1]
	v_add_f32_e32 v12, v78, v15
	v_fma_mix_f32 v44, v12, s76, -v95 op_sel:[0,0,1] op_sel_hi:[0,0,1]
	v_add_f32_e32 v12, v79, v17
	v_mul_f32_e32 v26, 0.5, v12
	v_add_f32_e32 v12, v80, v18
	v_mul_f32_e32 v25, 0.5, v12
	v_add_f32_e32 v12, v81, v19
	v_mul_f32_e32 v1, 0x45800000, v0
	v_mul_f32_e32 v24, 0.5, v12
	v_add_f32_e32 v12, v82, v22
	v_cndmask_b32_e32 v31, v0, v1, vcc
	v_mul_f32_e32 v70, 0.5, v12
	v_cvt_f32_f16_e32 v42, v94
	v_cvt_f32_f16_sdwa v40, v94 dst_sel:DWORD dst_unused:UNUSED_PAD src0_sel:WORD_1
	v_cvt_f32_f16_e32 v38, v95
	v_cvt_f32_f16_sdwa v36, v95 dst_sel:DWORD dst_unused:UNUSED_PAD src0_sel:WORD_1
	v_mul_f32_e32 v22, v16, v83
	s_nop 0
	v_pk_mul_f32 v[8:9], v[8:9], v[66:67]
	v_mul_f32_e32 v53, v61, v31
	v_mul_f32_e32 v47, v59, v31
	v_mul_f32_e32 v55, v60, v31
	v_mul_f32_e32 v45, v58, v31
	s_add_i32 s0, s0, s82
	s_cmpk_lt_i32 s0, 0x6000
	s_waitcnt vmcnt(0)
	v_fma_f32 v12, v22, v208, 0
	v_mul_f32_e32 v22, v29, v84
	v_fmac_f32_e32 v12, v22, v209
	v_mul_f32_e32 v13, v37, v35
	v_fmac_f32_e32 v12, v13, v210
	v_mul_f32_e32 v13, v39, v33
	v_fmac_f32_e32 v12, v13, v211
	v_pk_mul_f32 v[8:9], v[8:9], v[212:213]
	s_nop 0
	v_add_f32_e32 v8, v12, v8
	v_add_f32_e32 v12, v8, v9
	v_pk_mul_f32 v[8:9], v[10:11], v[68:69]
	s_nop 0
	v_pk_mul_f32 v[8:9], v[8:9], v[214:215]
	s_nop 0
	v_add_f32_e32 v8, v12, v8
	v_add_f32_e32 v8, v8, v9
	s_nop 1
	v_add_f32_dpp v8, v8, v8 quad_perm:[1,0,3,2] row_mask:0xf bank_mask:0xf bound_ctrl:1
	s_nop 1
	v_add_f32_dpp v8, v8, v8 quad_perm:[2,3,0,1] row_mask:0xf bank_mask:0xf bound_ctrl:1
	s_nop 1
	v_add_f32_dpp v66, v8, v8 row_half_mirror row_mask:0xf bank_mask:0xf bound_ctrl:1
	v_mov_b32_e32 v64, v204
	s_nop 0
	v_readlane_b32 s1, v254, 9
	v_lshlrev_b32_e32 v27, 16, v118
	v_and_b32_e32 v29, 0xffff0000, v118
	v_lshlrev_b32_e32 v33, 16, v119
	v_and_b32_e32 v35, 0xffff0000, v119
	v_lshlrev_b32_e32 v67, 16, v134
	v_and_b32_e32 v68, 0xffff0000, v134
	v_lshlrev_b32_e32 v69, 16, v135
	v_and_b32_e32 v71, 0xffff0000, v135
	s_nop 0
	s_nop 0
	v_add_u32_e32 v72, s1, v72
	v_mov_b32_e32 v65, v220
	v_mov_b32_e32 v16, v205
	v_mov_b32_e32 v41, v229
	v_mov_b32_e32 v17, v221
	v_pk_fma_f32 v[4:5], v[16:17], v[52:53], v[40:41]
	v_mov_b32_e32 v39, v230
	v_fmac_f32_e32 v5, v4, v66
	v_mul_f32_e32 v21, v5, v29
	v_mov_b32_e32 v4, v206
	v_mov_b32_e32 v5, v222
	v_mov_b32_e32 v43, v228
	v_pk_fma_f32 v[4:5], v[4:5], v[46:47], v[38:39]
	v_pk_fma_f32 v[42:43], v[64:65], v[54:55], v[42:43]
	v_fmac_f32_e32 v5, v4, v66
	v_mov_b32_e32 v18, v207
	v_mov_b32_e32 v37, v231
	v_fmac_f32_e32 v43, v42, v66
	v_mul_f32_e32 v22, v5, v33
	v_mov_b32_e32 v19, v223
	v_pk_fma_f32 v[4:5], v[18:19], v[44:45], v[36:37]
	v_mul_f32_e32 v20, v43, v27
	v_fmac_f32_e32 v5, v4, v66
	v_mov_b32_e32 v27, v57
	v_mul_f32_e32 v18, v5, v35
	v_pk_add_f32 v[4:5], v[26:27], v[30:31] neg_lo:[0,1] neg_hi:[0,1]
	v_pk_mul_f32 v[6:7], v[56:57], v[30:31]
	v_mov_b32_e32 v16, v30
	v_mov_b32_e32 v5, v7
	v_mov_b32_e32 v6, v200
	v_mov_b32_e32 v7, v216
	v_mov_b32_e32 v17, v224
	v_pk_fma_f32 v[4:5], v[4:5], v[6:7], v[16:17]
	v_mov_b32_e32 v35, v31
	v_fmac_f32_e32 v5, v4, v66
	v_pk_mul_f32 v[6:7], v[56:57], v[34:35] op_sel_hi:[0,1]
	v_mul_f32_e32 v12, v5, v67
	v_sub_f32_e32 v4, v25, v34
	v_mov_b32_e32 v5, v7
	v_mov_b32_e32 v8, v201
	v_mov_b32_e32 v35, v225
	v_mov_b32_e32 v9, v217
	v_pk_fma_f32 v[0:1], v[4:5], v[8:9], v[34:35]
	v_mov_b32_e32 v25, v49
	v_fmac_f32_e32 v1, v0, v66
	v_mov_b32_e32 v33, v31
	v_mul_f32_e32 v6, v1, v68
	v_pk_add_f32 v[0:1], v[24:25], v[32:33] neg_lo:[0,1] neg_hi:[0,1]
	v_pk_mul_f32 v[4:5], v[48:49], v[32:33]
	v_mov_b32_e32 v33, v226
	v_mov_b32_e32 v1, v5
	v_mov_b32_e32 v4, v202
	v_mov_b32_e32 v5, v218
	v_pk_fma_f32 v[0:1], v[0:1], v[4:5], v[32:33]
	v_mov_b32_e32 v29, v31
	v_fmac_f32_e32 v1, v0, v66
	v_pk_mul_f32 v[4:5], v[48:49], v[28:29] op_sel_hi:[0,1]
	v_mul_f32_e32 v7, v1, v69
	v_sub_f32_e32 v0, v70, v28
	v_mov_b32_e32 v1, v5
	v_mov_b32_e32 v10, v203
	v_mov_b32_e32 v29, v227
	v_mov_b32_e32 v11, v219
	v_pk_fma_f32 v[0:1], v[0:1], v[10:11], v[28:29]
	s_nop 0
	v_fmac_f32_e32 v1, v0, v66
	v_mul_f32_e32 v3, v1, v71
	v_cvt_pk_bf16_f32 v0, v20, v21
	v_cvt_pk_bf16_f32 v1, v22, v18
	v_cvt_pk_bf16_f32 v2, v12, v6
	v_cvt_pk_bf16_f32 v3, v7, v3
	global_store_dwordx4 v[62:63], v[0:3], off offset:1280
	s_cbranch_scc1 .LBB0_1418
